# K-loop LDS fragment base addresses computed once per unit
# baseline (speedup 1.0000x reference)
.LBB0_691:
	s_add_u32 s57, s10, 0x100
	s_addc_u32 vcc_lo, s11, 0
	s_add_u32 s38, s52, 0x80
	s_addc_u32 s39, s53, 0
	s_mov_b32 s10, 0
	s_add_i32 s52, s10, 2
	s_add_u32 s33, s38, 0x80
	s_addc_u32 s11, s39, 0
	s_add_i32 s34, 0, 0x10000
	s_cmp_eq_u32 s95, s10
	s_cselect_b32 s11, s9, s11
	s_cselect_b32 s10, s8, s33
	s_cselect_b32 s73, s1, vcc_lo
	s_cselect_b32 s72, s0, s57
	s_add_i32 s33, 0, 0x14000
	v_add_u32_e32 v230, s34, v223
	v_add_u32_e32 v231, s33, v223
	ds_read_b128 v[130:133], v230
	ds_read_b128 v[134:137], v230 offset:1024
	ds_read_b128 v[138:141], v230 offset:2048
	ds_read_b128 v[156:159], v230 offset:3072
	ds_read_b128 v[160:163], v231
	ds_read_b128 v[164:167], v231 offset:1024
	ds_read_b128 v[168:171], v231 offset:2048
	ds_read_b128 v[172:175], v231 offset:3072
	s_add_i32 m0, s20, 0xc000
	ds_read_b128 v[176:179], v225
	ds_read_b128 v[180:183], v225 offset:1024
	ds_read_b128 v[184:187], v225 offset:2048
	ds_read_b128 v[188:191], v225 offset:3072
	ds_read_b128 v[192:195], v225 offset:4096
	ds_read_b128 v[196:199], v225 offset:5120
	ds_read_b128 v[200:203], v225 offset:6144
	ds_read_b128 v[226:229], v225 offset:7168
	global_load_lds_dwordx4 v154, s[38:39]
	s_add_i32 m0, s20, 0xe000
	s_nop 0
	global_load_lds_dwordx4 v152, s[38:39]
	s_waitcnt vmcnt(8)
	s_waitcnt lgkmcnt(0)
	s_barrier
	s_setprio 1
	s_waitcnt lgkmcnt(0)
	v_mfma_f32_16x16x32_bf16 v[126:129], v[130:133], v[176:179], 0
	v_mfma_f32_16x16x32_bf16 v[122:125], v[138:141], v[176:179], 0
	v_mfma_f32_16x16x32_bf16 v[110:113], v[130:133], v[184:187], 0
	v_mfma_f32_16x16x32_bf16 v[106:109], v[138:141], v[184:187], 0
	v_mfma_f32_16x16x32_bf16 v[94:97], v[130:133], v[192:195], 0
	v_mfma_f32_16x16x32_bf16 v[90:93], v[138:141], v[192:195], 0
	v_mfma_f32_16x16x32_bf16 v[78:81], v[130:133], v[200:203], 0
	v_mfma_f32_16x16x32_bf16 v[74:77], v[138:141], v[200:203], 0
	v_mfma_f32_16x16x32_bf16 v[126:129], v[134:137], v[180:183], v[126:129]
	v_mfma_f32_16x16x32_bf16 v[122:125], v[156:159], v[180:183], v[122:125]
	v_mfma_f32_16x16x32_bf16 v[110:113], v[134:137], v[188:191], v[110:113]
	v_mfma_f32_16x16x32_bf16 v[106:109], v[156:159], v[188:191], v[106:109]
	v_mfma_f32_16x16x32_bf16 v[94:97], v[134:137], v[196:199], v[94:97]
	v_mfma_f32_16x16x32_bf16 v[90:93], v[156:159], v[196:199], v[90:93]
	v_mfma_f32_16x16x32_bf16 v[78:81], v[134:137], v[226:229], v[78:81]
	v_mfma_f32_16x16x32_bf16 v[74:77], v[156:159], v[226:229], v[74:77]
	s_setprio 0
	s_setprio 1
	v_mfma_f32_16x16x32_bf16 v[118:121], v[160:163], v[176:179], 0
	v_mfma_f32_16x16x32_bf16 v[114:117], v[168:171], v[176:179], 0
	v_mfma_f32_16x16x32_bf16 v[102:105], v[160:163], v[184:187], 0
	v_mfma_f32_16x16x32_bf16 v[98:101], v[168:171], v[184:187], 0
	v_mfma_f32_16x16x32_bf16 v[86:89], v[160:163], v[192:195], 0
	v_mfma_f32_16x16x32_bf16 v[82:85], v[168:171], v[192:195], 0
	v_mfma_f32_16x16x32_bf16 v[70:73], v[160:163], v[200:203], 0
	v_mfma_f32_16x16x32_bf16 v[66:69], v[168:171], v[200:203], 0
	v_mfma_f32_16x16x32_bf16 v[118:121], v[164:167], v[180:183], v[118:121]
	v_mfma_f32_16x16x32_bf16 v[114:117], v[172:175], v[180:183], v[114:117]
	v_mfma_f32_16x16x32_bf16 v[102:105], v[164:167], v[188:191], v[102:105]
	v_mfma_f32_16x16x32_bf16 v[98:101], v[172:175], v[188:191], v[98:101]
	v_mfma_f32_16x16x32_bf16 v[86:89], v[164:167], v[196:199], v[86:89]
	v_mfma_f32_16x16x32_bf16 v[82:85], v[172:175], v[196:199], v[82:85]
	v_mfma_f32_16x16x32_bf16 v[70:73], v[164:167], v[226:229], v[70:73]
	v_mfma_f32_16x16x32_bf16 v[66:69], v[172:175], v[226:229], v[66:69]
	s_setprio 0
	s_barrier
	s_add_i32 s34, s34, s29
	s_mov_b32 m0, s34
	ds_read_b128 v[176:179], v225 offset:16384
	ds_read_b128 v[180:183], v225 offset:17408
	ds_read_b128 v[184:187], v225 offset:18432
	ds_read_b128 v[188:191], v225 offset:19456
	ds_read_b128 v[192:195], v225 offset:20480
	ds_read_b128 v[196:199], v225 offset:21504
	ds_read_b128 v[200:203], v225 offset:22528
	ds_read_b128 v[226:229], v225 offset:23552
	global_load_lds_dwordx4 v0, s[72:73]
	s_add_i32 m0, s34, 0x2000
	s_mov_b64 s[98:99], s[72:73]
	s_add_i32 s33, s33, s29
	global_load_lds_dwordx4 v150, s[72:73]
	s_add_u32 s72, s72, s46
	s_addc_u32 s73, s73, 0
	s_mov_b32 m0, s33
	s_mov_b64 s[100:101], s[10:11]
	global_load_lds_dwordx4 v0, s[72:73]
	s_add_i32 m0, s33, 0x2000
	s_nop 0
	global_load_lds_dwordx4 v150, s[72:73]
	s_mov_b32 m0, s20
	s_nop 0
	global_load_lds_dwordx4 v146, s[10:11]
	s_mov_b32 m0, s35
	s_nop 0
	global_load_lds_dwordx4 v148, s[10:11]
	s_waitcnt vmcnt(8)
	s_waitcnt lgkmcnt(0)
	s_barrier
	s_setprio 1
	s_waitcnt lgkmcnt(0)
	v_mfma_f32_16x16x32_bf16 v[62:65], v[130:133], v[176:179], 0
	v_mfma_f32_16x16x32_bf16 v[58:61], v[138:141], v[176:179], 0
	v_mfma_f32_16x16x32_bf16 v[46:49], v[130:133], v[184:187], 0
	v_mfma_f32_16x16x32_bf16 v[42:45], v[138:141], v[184:187], 0
	v_mfma_f32_16x16x32_bf16 v[30:33], v[130:133], v[192:195], 0
	v_mfma_f32_16x16x32_bf16 v[26:29], v[138:141], v[192:195], 0
	v_mfma_f32_16x16x32_bf16 v[14:17], v[130:133], v[200:203], 0
	v_mfma_f32_16x16x32_bf16 v[10:13], v[138:141], v[200:203], 0
	v_mfma_f32_16x16x32_bf16 v[62:65], v[134:137], v[180:183], v[62:65]
	v_mfma_f32_16x16x32_bf16 v[58:61], v[156:159], v[180:183], v[58:61]
	v_mfma_f32_16x16x32_bf16 v[46:49], v[134:137], v[188:191], v[46:49]
	v_mfma_f32_16x16x32_bf16 v[42:45], v[156:159], v[188:191], v[42:45]
	v_mfma_f32_16x16x32_bf16 v[30:33], v[134:137], v[196:199], v[30:33]
	v_mfma_f32_16x16x32_bf16 v[26:29], v[156:159], v[196:199], v[26:29]
	v_mfma_f32_16x16x32_bf16 v[14:17], v[134:137], v[226:229], v[14:17]
	v_mfma_f32_16x16x32_bf16 v[10:13], v[156:159], v[226:229], v[10:13]
	s_setprio 0
	s_setprio 1
	v_mfma_f32_16x16x32_bf16 v[54:57], v[160:163], v[176:179], 0
	v_mfma_f32_16x16x32_bf16 v[50:53], v[168:171], v[176:179], 0
	v_mfma_f32_16x16x32_bf16 v[38:41], v[160:163], v[184:187], 0
	v_mfma_f32_16x16x32_bf16 v[34:37], v[168:171], v[184:187], 0
	v_mfma_f32_16x16x32_bf16 v[22:25], v[160:163], v[192:195], 0
	v_mfma_f32_16x16x32_bf16 v[18:21], v[168:171], v[192:195], 0
	v_mfma_f32_16x16x32_bf16 v[6:9], v[160:163], v[200:203], 0
	v_mfma_f32_16x16x32_bf16 v[2:5], v[168:171], v[200:203], 0
	v_mfma_f32_16x16x32_bf16 v[54:57], v[164:167], v[180:183], v[54:57]
	v_mfma_f32_16x16x32_bf16 v[50:53], v[172:175], v[180:183], v[50:53]
	v_mfma_f32_16x16x32_bf16 v[38:41], v[164:167], v[188:191], v[38:41]
	v_mfma_f32_16x16x32_bf16 v[34:37], v[172:175], v[188:191], v[34:37]
	v_mfma_f32_16x16x32_bf16 v[22:25], v[164:167], v[196:199], v[22:25]
	v_mfma_f32_16x16x32_bf16 v[18:21], v[172:175], v[196:199], v[18:21]
	v_mfma_f32_16x16x32_bf16 v[6:9], v[164:167], v[226:229], v[6:9]
	v_mfma_f32_16x16x32_bf16 v[2:5], v[172:175], v[226:229], v[2:5]
	s_setprio 0
	s_barrier
	s_add_i32 s33, 0, 0x18000
	s_add_i32 s34, 0, 0x1c000
	v_add_u32_e32 v232, s33, v223
	v_add_u32_e32 v233, s34, v223
	ds_read_b128 v[130:133], v232
	ds_read_b128 v[134:137], v232 offset:1024
	ds_read_b128 v[138:141], v232 offset:2048
	ds_read_b128 v[156:159], v232 offset:3072
	ds_read_b128 v[160:163], v233
	ds_read_b128 v[164:167], v233 offset:1024
	ds_read_b128 v[168:171], v233 offset:2048
	ds_read_b128 v[172:175], v233 offset:3072
	s_add_u32 s10, s10, s46
	s_addc_u32 s11, s11, 0
	s_mov_b32 m0, s93
	ds_read_b128 v[176:179], v225 offset:32768
	ds_read_b128 v[180:183], v225 offset:33792
	ds_read_b128 v[184:187], v225 offset:34816
	ds_read_b128 v[188:191], v225 offset:35840
	ds_read_b128 v[192:195], v225 offset:36864
	ds_read_b128 v[196:199], v225 offset:37888
	ds_read_b128 v[200:203], v225 offset:38912
	ds_read_b128 v[226:229], v225 offset:39936
	global_load_lds_dwordx4 v146, s[10:11]
	s_mov_b32 m0, s83
	s_nop 0
	global_load_lds_dwordx4 v148, s[10:11]
	s_waitcnt vmcnt(8)
	s_waitcnt lgkmcnt(0)
	s_barrier
	s_setprio 1
	s_waitcnt lgkmcnt(0)
	v_mfma_f32_16x16x32_bf16 v[126:129], v[130:133], v[176:179], v[126:129]
	v_mfma_f32_16x16x32_bf16 v[122:125], v[138:141], v[176:179], v[122:125]
	v_mfma_f32_16x16x32_bf16 v[110:113], v[130:133], v[184:187], v[110:113]
	v_mfma_f32_16x16x32_bf16 v[106:109], v[138:141], v[184:187], v[106:109]
	v_mfma_f32_16x16x32_bf16 v[94:97], v[130:133], v[192:195], v[94:97]
	v_mfma_f32_16x16x32_bf16 v[90:93], v[138:141], v[192:195], v[90:93]
	v_mfma_f32_16x16x32_bf16 v[78:81], v[130:133], v[200:203], v[78:81]
	v_mfma_f32_16x16x32_bf16 v[74:77], v[138:141], v[200:203], v[74:77]
	v_mfma_f32_16x16x32_bf16 v[126:129], v[134:137], v[180:183], v[126:129]
	v_mfma_f32_16x16x32_bf16 v[122:125], v[156:159], v[180:183], v[122:125]
	v_mfma_f32_16x16x32_bf16 v[110:113], v[134:137], v[188:191], v[110:113]
	v_mfma_f32_16x16x32_bf16 v[106:109], v[156:159], v[188:191], v[106:109]
	v_mfma_f32_16x16x32_bf16 v[94:97], v[134:137], v[196:199], v[94:97]
	v_mfma_f32_16x16x32_bf16 v[90:93], v[156:159], v[196:199], v[90:93]
	v_mfma_f32_16x16x32_bf16 v[78:81], v[134:137], v[226:229], v[78:81]
	v_mfma_f32_16x16x32_bf16 v[74:77], v[156:159], v[226:229], v[74:77]
	s_setprio 0
	s_setprio 1
	v_mfma_f32_16x16x32_bf16 v[118:121], v[160:163], v[176:179], v[118:121]
	v_mfma_f32_16x16x32_bf16 v[114:117], v[168:171], v[176:179], v[114:117]
	v_mfma_f32_16x16x32_bf16 v[102:105], v[160:163], v[184:187], v[102:105]
	v_mfma_f32_16x16x32_bf16 v[98:101], v[168:171], v[184:187], v[98:101]
	v_mfma_f32_16x16x32_bf16 v[86:89], v[160:163], v[192:195], v[86:89]
	v_mfma_f32_16x16x32_bf16 v[82:85], v[168:171], v[192:195], v[82:85]
	v_mfma_f32_16x16x32_bf16 v[70:73], v[160:163], v[200:203], v[70:73]
	v_mfma_f32_16x16x32_bf16 v[66:69], v[168:171], v[200:203], v[66:69]
	v_mfma_f32_16x16x32_bf16 v[118:121], v[164:167], v[180:183], v[118:121]
	v_mfma_f32_16x16x32_bf16 v[114:117], v[172:175], v[180:183], v[114:117]
	v_mfma_f32_16x16x32_bf16 v[102:105], v[164:167], v[188:191], v[102:105]
	v_mfma_f32_16x16x32_bf16 v[98:101], v[172:175], v[188:191], v[98:101]
	v_mfma_f32_16x16x32_bf16 v[86:89], v[164:167], v[196:199], v[86:89]
	v_mfma_f32_16x16x32_bf16 v[82:85], v[172:175], v[196:199], v[82:85]
	v_mfma_f32_16x16x32_bf16 v[70:73], v[164:167], v[226:229], v[70:73]
	v_mfma_f32_16x16x32_bf16 v[66:69], v[172:175], v[226:229], v[66:69]
	s_setprio 0
	s_barrier
	s_add_i32 s10, s33, s29
	s_mov_b32 m0, s10
	s_add_u32 s98, s98, 0x80
	s_addc_u32 s99, s99, 0
	ds_read_b128 v[176:179], v225 offset:49152
	ds_read_b128 v[180:183], v225 offset:50176
	ds_read_b128 v[184:187], v225 offset:51200
	ds_read_b128 v[188:191], v225 offset:52224
	ds_read_b128 v[192:195], v225 offset:53248
	ds_read_b128 v[196:199], v225 offset:54272
	ds_read_b128 v[200:203], v225 offset:55296
	ds_read_b128 v[226:229], v225 offset:56320
	global_load_lds_dwordx4 v0, s[98:99]
	s_add_i32 m0, s10, 0x2000
	s_add_i32 s10, s34, s29
	global_load_lds_dwordx4 v150, s[98:99]
	s_mov_b32 m0, s10
	s_add_u32 s72, s72, 0x80
	s_addc_u32 s73, s73, 0
	global_load_lds_dwordx4 v0, s[72:73]
	s_add_i32 m0, s10, 0x2000
	s_add_u32 s100, s100, 0x80
	s_addc_u32 s101, s101, 0
	global_load_lds_dwordx4 v150, s[72:73]
	s_mov_b32 m0, s96
	s_nop 0
	global_load_lds_dwordx4 v146, s[100:101]
	s_mov_b32 m0, s97
	s_nop 0
	global_load_lds_dwordx4 v148, s[100:101]
	s_waitcnt vmcnt(8)
	s_waitcnt lgkmcnt(0)
	s_barrier
	s_setprio 1
	s_waitcnt lgkmcnt(0)
	v_mfma_f32_16x16x32_bf16 v[62:65], v[130:133], v[176:179], v[62:65]
	v_mfma_f32_16x16x32_bf16 v[58:61], v[138:141], v[176:179], v[58:61]
	v_mfma_f32_16x16x32_bf16 v[46:49], v[130:133], v[184:187], v[46:49]
	v_mfma_f32_16x16x32_bf16 v[42:45], v[138:141], v[184:187], v[42:45]
	v_mfma_f32_16x16x32_bf16 v[30:33], v[130:133], v[192:195], v[30:33]
	v_mfma_f32_16x16x32_bf16 v[26:29], v[138:141], v[192:195], v[26:29]
	v_mfma_f32_16x16x32_bf16 v[14:17], v[130:133], v[200:203], v[14:17]
	v_mfma_f32_16x16x32_bf16 v[10:13], v[138:141], v[200:203], v[10:13]
	v_mfma_f32_16x16x32_bf16 v[62:65], v[134:137], v[180:183], v[62:65]
	v_mfma_f32_16x16x32_bf16 v[58:61], v[156:159], v[180:183], v[58:61]
	v_mfma_f32_16x16x32_bf16 v[46:49], v[134:137], v[188:191], v[46:49]
	v_mfma_f32_16x16x32_bf16 v[42:45], v[156:159], v[188:191], v[42:45]
	v_mfma_f32_16x16x32_bf16 v[30:33], v[134:137], v[196:199], v[30:33]
	v_mfma_f32_16x16x32_bf16 v[26:29], v[156:159], v[196:199], v[26:29]
	v_mfma_f32_16x16x32_bf16 v[14:17], v[134:137], v[226:229], v[14:17]
	v_mfma_f32_16x16x32_bf16 v[10:13], v[156:159], v[226:229], v[10:13]
	s_setprio 0
	s_setprio 1
	v_mfma_f32_16x16x32_bf16 v[54:57], v[160:163], v[176:179], v[54:57]
	v_mfma_f32_16x16x32_bf16 v[50:53], v[168:171], v[176:179], v[50:53]
	v_mfma_f32_16x16x32_bf16 v[38:41], v[160:163], v[184:187], v[38:41]
	v_mfma_f32_16x16x32_bf16 v[34:37], v[168:171], v[184:187], v[34:37]
	v_mfma_f32_16x16x32_bf16 v[22:25], v[160:163], v[192:195], v[22:25]
	v_mfma_f32_16x16x32_bf16 v[18:21], v[168:171], v[192:195], v[18:21]
	v_mfma_f32_16x16x32_bf16 v[6:9], v[160:163], v[200:203], v[6:9]
	v_mfma_f32_16x16x32_bf16 v[2:5], v[168:171], v[200:203], v[2:5]
	v_mfma_f32_16x16x32_bf16 v[54:57], v[164:167], v[180:183], v[54:57]
	v_mfma_f32_16x16x32_bf16 v[50:53], v[172:175], v[180:183], v[50:53]
	v_mfma_f32_16x16x32_bf16 v[38:41], v[164:167], v[188:191], v[38:41]
	v_mfma_f32_16x16x32_bf16 v[34:37], v[172:175], v[188:191], v[34:37]
	v_mfma_f32_16x16x32_bf16 v[22:25], v[164:167], v[196:199], v[22:25]
	v_mfma_f32_16x16x32_bf16 v[18:21], v[172:175], v[196:199], v[18:21]
	v_mfma_f32_16x16x32_bf16 v[6:9], v[164:167], v[226:229], v[6:9]
	v_mfma_f32_16x16x32_bf16 v[2:5], v[172:175], v[226:229], v[2:5]
	s_setprio 0
	s_barrier
	s_add_u32 s57, s57, 0x100
	s_addc_u32 vcc_lo, vcc_lo, 0
	s_add_u32 s38, s38, 0x100
	s_addc_u32 s39, s39, 0
	s_cmp_ge_u32 s52, s22
	s_mov_b32 s10, s52
	s_cbranch_scc0 .LBB0_692
	s_branch .Lkloop_exit
.LBB0_692:
	s_add_i32 s52, s10, 2
	s_add_u32 s33, s38, 0x80
	s_addc_u32 s11, s39, 0
	s_add_i32 s34, 0, 0x10000
	s_cmp_eq_u32 s95, s10
	s_cselect_b32 s11, s9, s11
	s_cselect_b32 s10, s8, s33
	s_cselect_b32 s73, s1, vcc_lo
	s_cselect_b32 s72, s0, s57
	s_add_i32 s33, 0, 0x14000
	ds_read_b128 v[130:133], v230
	ds_read_b128 v[134:137], v230 offset:1024
	ds_read_b128 v[138:141], v230 offset:2048
	ds_read_b128 v[156:159], v230 offset:3072
	ds_read_b128 v[160:163], v231
	ds_read_b128 v[164:167], v231 offset:1024
	ds_read_b128 v[168:171], v231 offset:2048
	ds_read_b128 v[172:175], v231 offset:3072
	s_add_i32 m0, s20, 0xc000
	ds_read_b128 v[176:179], v225
	ds_read_b128 v[180:183], v225 offset:1024
	ds_read_b128 v[184:187], v225 offset:2048
	ds_read_b128 v[188:191], v225 offset:3072
	ds_read_b128 v[192:195], v225 offset:4096
	ds_read_b128 v[196:199], v225 offset:5120
	ds_read_b128 v[200:203], v225 offset:6144
	ds_read_b128 v[226:229], v225 offset:7168
	global_load_lds_dwordx4 v154, s[38:39]
	s_add_i32 m0, s20, 0xe000
	s_nop 0
	global_load_lds_dwordx4 v152, s[38:39]
	s_waitcnt vmcnt(8)
	s_waitcnt lgkmcnt(0)
	s_barrier
	s_setprio 1
	s_waitcnt lgkmcnt(0)
	v_mfma_f32_16x16x32_bf16 v[126:129], v[130:133], v[176:179], v[126:129]
	v_mfma_f32_16x16x32_bf16 v[122:125], v[138:141], v[176:179], v[122:125]
	v_mfma_f32_16x16x32_bf16 v[110:113], v[130:133], v[184:187], v[110:113]
	v_mfma_f32_16x16x32_bf16 v[106:109], v[138:141], v[184:187], v[106:109]
	v_mfma_f32_16x16x32_bf16 v[94:97], v[130:133], v[192:195], v[94:97]
	v_mfma_f32_16x16x32_bf16 v[90:93], v[138:141], v[192:195], v[90:93]
	v_mfma_f32_16x16x32_bf16 v[78:81], v[130:133], v[200:203], v[78:81]
	v_mfma_f32_16x16x32_bf16 v[74:77], v[138:141], v[200:203], v[74:77]
	v_mfma_f32_16x16x32_bf16 v[126:129], v[134:137], v[180:183], v[126:129]
	v_mfma_f32_16x16x32_bf16 v[122:125], v[156:159], v[180:183], v[122:125]
	v_mfma_f32_16x16x32_bf16 v[110:113], v[134:137], v[188:191], v[110:113]
	v_mfma_f32_16x16x32_bf16 v[106:109], v[156:159], v[188:191], v[106:109]
	v_mfma_f32_16x16x32_bf16 v[94:97], v[134:137], v[196:199], v[94:97]
	v_mfma_f32_16x16x32_bf16 v[90:93], v[156:159], v[196:199], v[90:93]
	v_mfma_f32_16x16x32_bf16 v[78:81], v[134:137], v[226:229], v[78:81]
	v_mfma_f32_16x16x32_bf16 v[74:77], v[156:159], v[226:229], v[74:77]
	s_setprio 0
	s_setprio 1
	v_mfma_f32_16x16x32_bf16 v[118:121], v[160:163], v[176:179], v[118:121]
	v_mfma_f32_16x16x32_bf16 v[114:117], v[168:171], v[176:179], v[114:117]
	v_mfma_f32_16x16x32_bf16 v[102:105], v[160:163], v[184:187], v[102:105]
	v_mfma_f32_16x16x32_bf16 v[98:101], v[168:171], v[184:187], v[98:101]
	v_mfma_f32_16x16x32_bf16 v[86:89], v[160:163], v[192:195], v[86:89]
	v_mfma_f32_16x16x32_bf16 v[82:85], v[168:171], v[192:195], v[82:85]
	v_mfma_f32_16x16x32_bf16 v[70:73], v[160:163], v[200:203], v[70:73]
	v_mfma_f32_16x16x32_bf16 v[66:69], v[168:171], v[200:203], v[66:69]
	v_mfma_f32_16x16x32_bf16 v[118:121], v[164:167], v[180:183], v[118:121]
	v_mfma_f32_16x16x32_bf16 v[114:117], v[172:175], v[180:183], v[114:117]
	v_mfma_f32_16x16x32_bf16 v[102:105], v[164:167], v[188:191], v[102:105]
	v_mfma_f32_16x16x32_bf16 v[98:101], v[172:175], v[188:191], v[98:101]
	v_mfma_f32_16x16x32_bf16 v[86:89], v[164:167], v[196:199], v[86:89]
	v_mfma_f32_16x16x32_bf16 v[82:85], v[172:175], v[196:199], v[82:85]
	v_mfma_f32_16x16x32_bf16 v[70:73], v[164:167], v[226:229], v[70:73]
	v_mfma_f32_16x16x32_bf16 v[66:69], v[172:175], v[226:229], v[66:69]
	s_setprio 0
	s_barrier
	s_add_i32 s34, s34, s29
	s_mov_b32 m0, s34
	ds_read_b128 v[176:179], v225 offset:16384
	ds_read_b128 v[180:183], v225 offset:17408
	ds_read_b128 v[184:187], v225 offset:18432
	ds_read_b128 v[188:191], v225 offset:19456
	ds_read_b128 v[192:195], v225 offset:20480
	ds_read_b128 v[196:199], v225 offset:21504
	ds_read_b128 v[200:203], v225 offset:22528
	ds_read_b128 v[226:229], v225 offset:23552
	global_load_lds_dwordx4 v0, s[72:73]
	s_add_i32 m0, s34, 0x2000
	s_mov_b64 s[98:99], s[72:73]
	s_add_i32 s33, s33, s29
	global_load_lds_dwordx4 v150, s[72:73]
	s_add_u32 s72, s72, s46
	s_addc_u32 s73, s73, 0
	s_mov_b32 m0, s33
	s_mov_b64 s[100:101], s[10:11]
	global_load_lds_dwordx4 v0, s[72:73]
	s_add_i32 m0, s33, 0x2000
	s_nop 0
	global_load_lds_dwordx4 v150, s[72:73]
	s_mov_b32 m0, s20
	s_nop 0
	global_load_lds_dwordx4 v146, s[10:11]
	s_mov_b32 m0, s35
	s_nop 0
	global_load_lds_dwordx4 v148, s[10:11]
	s_waitcnt vmcnt(8)
	s_waitcnt lgkmcnt(0)
	s_barrier
	s_setprio 1
	s_waitcnt lgkmcnt(0)
	v_mfma_f32_16x16x32_bf16 v[62:65], v[130:133], v[176:179], v[62:65]
	v_mfma_f32_16x16x32_bf16 v[58:61], v[138:141], v[176:179], v[58:61]
	v_mfma_f32_16x16x32_bf16 v[46:49], v[130:133], v[184:187], v[46:49]
	v_mfma_f32_16x16x32_bf16 v[42:45], v[138:141], v[184:187], v[42:45]
	v_mfma_f32_16x16x32_bf16 v[30:33], v[130:133], v[192:195], v[30:33]
	v_mfma_f32_16x16x32_bf16 v[26:29], v[138:141], v[192:195], v[26:29]
	v_mfma_f32_16x16x32_bf16 v[14:17], v[130:133], v[200:203], v[14:17]
	v_mfma_f32_16x16x32_bf16 v[10:13], v[138:141], v[200:203], v[10:13]
	v_mfma_f32_16x16x32_bf16 v[62:65], v[134:137], v[180:183], v[62:65]
	v_mfma_f32_16x16x32_bf16 v[58:61], v[156:159], v[180:183], v[58:61]
	v_mfma_f32_16x16x32_bf16 v[46:49], v[134:137], v[188:191], v[46:49]
	v_mfma_f32_16x16x32_bf16 v[42:45], v[156:159], v[188:191], v[42:45]
	v_mfma_f32_16x16x32_bf16 v[30:33], v[134:137], v[196:199], v[30:33]
	v_mfma_f32_16x16x32_bf16 v[26:29], v[156:159], v[196:199], v[26:29]
	v_mfma_f32_16x16x32_bf16 v[14:17], v[134:137], v[226:229], v[14:17]
	v_mfma_f32_16x16x32_bf16 v[10:13], v[156:159], v[226:229], v[10:13]
	s_setprio 0
	s_setprio 1
	v_mfma_f32_16x16x32_bf16 v[54:57], v[160:163], v[176:179], v[54:57]
	v_mfma_f32_16x16x32_bf16 v[50:53], v[168:171], v[176:179], v[50:53]
	v_mfma_f32_16x16x32_bf16 v[38:41], v[160:163], v[184:187], v[38:41]
	v_mfma_f32_16x16x32_bf16 v[34:37], v[168:171], v[184:187], v[34:37]
	v_mfma_f32_16x16x32_bf16 v[22:25], v[160:163], v[192:195], v[22:25]
	v_mfma_f32_16x16x32_bf16 v[18:21], v[168:171], v[192:195], v[18:21]
	v_mfma_f32_16x16x32_bf16 v[6:9], v[160:163], v[200:203], v[6:9]
	v_mfma_f32_16x16x32_bf16 v[2:5], v[168:171], v[200:203], v[2:5]
	v_mfma_f32_16x16x32_bf16 v[54:57], v[164:167], v[180:183], v[54:57]
	v_mfma_f32_16x16x32_bf16 v[50:53], v[172:175], v[180:183], v[50:53]
	v_mfma_f32_16x16x32_bf16 v[38:41], v[164:167], v[188:191], v[38:41]
	v_mfma_f32_16x16x32_bf16 v[34:37], v[172:175], v[188:191], v[34:37]
	v_mfma_f32_16x16x32_bf16 v[22:25], v[164:167], v[196:199], v[22:25]
	v_mfma_f32_16x16x32_bf16 v[18:21], v[172:175], v[196:199], v[18:21]
	v_mfma_f32_16x16x32_bf16 v[6:9], v[164:167], v[226:229], v[6:9]
	v_mfma_f32_16x16x32_bf16 v[2:5], v[172:175], v[226:229], v[2:5]
	s_setprio 0
	s_barrier
	s_add_i32 s33, 0, 0x18000
	s_add_i32 s34, 0, 0x1c000
	ds_read_b128 v[130:133], v232
	ds_read_b128 v[134:137], v232 offset:1024
	ds_read_b128 v[138:141], v232 offset:2048
	ds_read_b128 v[156:159], v232 offset:3072
	ds_read_b128 v[160:163], v233
	ds_read_b128 v[164:167], v233 offset:1024
	ds_read_b128 v[168:171], v233 offset:2048
	ds_read_b128 v[172:175], v233 offset:3072
	s_add_u32 s10, s10, s46
	s_addc_u32 s11, s11, 0
	s_mov_b32 m0, s93
	ds_read_b128 v[176:179], v225 offset:32768
	ds_read_b128 v[180:183], v225 offset:33792
	ds_read_b128 v[184:187], v225 offset:34816
	ds_read_b128 v[188:191], v225 offset:35840
	ds_read_b128 v[192:195], v225 offset:36864
	ds_read_b128 v[196:199], v225 offset:37888
	ds_read_b128 v[200:203], v225 offset:38912
	ds_read_b128 v[226:229], v225 offset:39936
	global_load_lds_dwordx4 v146, s[10:11]
	s_mov_b32 m0, s83
	s_nop 0
	global_load_lds_dwordx4 v148, s[10:11]
	s_waitcnt vmcnt(8)
	s_waitcnt lgkmcnt(0)
	s_barrier
	s_setprio 1
	s_waitcnt lgkmcnt(0)
	v_mfma_f32_16x16x32_bf16 v[126:129], v[130:133], v[176:179], v[126:129]
	v_mfma_f32_16x16x32_bf16 v[122:125], v[138:141], v[176:179], v[122:125]
	v_mfma_f32_16x16x32_bf16 v[110:113], v[130:133], v[184:187], v[110:113]
	v_mfma_f32_16x16x32_bf16 v[106:109], v[138:141], v[184:187], v[106:109]
	v_mfma_f32_16x16x32_bf16 v[94:97], v[130:133], v[192:195], v[94:97]
	v_mfma_f32_16x16x32_bf16 v[90:93], v[138:141], v[192:195], v[90:93]
	v_mfma_f32_16x16x32_bf16 v[78:81], v[130:133], v[200:203], v[78:81]
	v_mfma_f32_16x16x32_bf16 v[74:77], v[138:141], v[200:203], v[74:77]
	v_mfma_f32_16x16x32_bf16 v[126:129], v[134:137], v[180:183], v[126:129]
	v_mfma_f32_16x16x32_bf16 v[122:125], v[156:159], v[180:183], v[122:125]
	v_mfma_f32_16x16x32_bf16 v[110:113], v[134:137], v[188:191], v[110:113]
	v_mfma_f32_16x16x32_bf16 v[106:109], v[156:159], v[188:191], v[106:109]
	v_mfma_f32_16x16x32_bf16 v[94:97], v[134:137], v[196:199], v[94:97]
	v_mfma_f32_16x16x32_bf16 v[90:93], v[156:159], v[196:199], v[90:93]
	v_mfma_f32_16x16x32_bf16 v[78:81], v[134:137], v[226:229], v[78:81]
	v_mfma_f32_16x16x32_bf16 v[74:77], v[156:159], v[226:229], v[74:77]
	s_setprio 0
	s_setprio 1
	v_mfma_f32_16x16x32_bf16 v[118:121], v[160:163], v[176:179], v[118:121]
	v_mfma_f32_16x16x32_bf16 v[114:117], v[168:171], v[176:179], v[114:117]
	v_mfma_f32_16x16x32_bf16 v[102:105], v[160:163], v[184:187], v[102:105]
	v_mfma_f32_16x16x32_bf16 v[98:101], v[168:171], v[184:187], v[98:101]
	v_mfma_f32_16x16x32_bf16 v[86:89], v[160:163], v[192:195], v[86:89]
	v_mfma_f32_16x16x32_bf16 v[82:85], v[168:171], v[192:195], v[82:85]
	v_mfma_f32_16x16x32_bf16 v[70:73], v[160:163], v[200:203], v[70:73]
	v_mfma_f32_16x16x32_bf16 v[66:69], v[168:171], v[200:203], v[66:69]
	v_mfma_f32_16x16x32_bf16 v[118:121], v[164:167], v[180:183], v[118:121]
	v_mfma_f32_16x16x32_bf16 v[114:117], v[172:175], v[180:183], v[114:117]
	v_mfma_f32_16x16x32_bf16 v[102:105], v[164:167], v[188:191], v[102:105]
	v_mfma_f32_16x16x32_bf16 v[98:101], v[172:175], v[188:191], v[98:101]
	v_mfma_f32_16x16x32_bf16 v[86:89], v[164:167], v[196:199], v[86:89]
	v_mfma_f32_16x16x32_bf16 v[82:85], v[172:175], v[196:199], v[82:85]
	v_mfma_f32_16x16x32_bf16 v[70:73], v[164:167], v[226:229], v[70:73]
	v_mfma_f32_16x16x32_bf16 v[66:69], v[172:175], v[226:229], v[66:69]
	s_setprio 0
	s_barrier
	s_add_i32 s10, s33, s29
	s_mov_b32 m0, s10
	s_add_u32 s98, s98, 0x80
	s_addc_u32 s99, s99, 0
	ds_read_b128 v[176:179], v225 offset:49152
	ds_read_b128 v[180:183], v225 offset:50176
	ds_read_b128 v[184:187], v225 offset:51200
	ds_read_b128 v[188:191], v225 offset:52224
	ds_read_b128 v[192:195], v225 offset:53248
	ds_read_b128 v[196:199], v225 offset:54272
	ds_read_b128 v[200:203], v225 offset:55296
	ds_read_b128 v[226:229], v225 offset:56320
	global_load_lds_dwordx4 v0, s[98:99]
	s_add_i32 m0, s10, 0x2000
	s_add_i32 s10, s34, s29
	global_load_lds_dwordx4 v150, s[98:99]
	s_mov_b32 m0, s10
	s_add_u32 s72, s72, 0x80
	s_addc_u32 s73, s73, 0
	global_load_lds_dwordx4 v0, s[72:73]
	s_add_i32 m0, s10, 0x2000
	s_add_u32 s100, s100, 0x80
	s_addc_u32 s101, s101, 0
	global_load_lds_dwordx4 v150, s[72:73]
	s_mov_b32 m0, s96
	s_nop 0
	global_load_lds_dwordx4 v146, s[100:101]
	s_mov_b32 m0, s97
	s_nop 0
	global_load_lds_dwordx4 v148, s[100:101]
	s_waitcnt vmcnt(8)
	s_waitcnt lgkmcnt(0)
	s_barrier
	s_setprio 1
	s_waitcnt lgkmcnt(0)
	v_mfma_f32_16x16x32_bf16 v[62:65], v[130:133], v[176:179], v[62:65]
	v_mfma_f32_16x16x32_bf16 v[58:61], v[138:141], v[176:179], v[58:61]
	v_mfma_f32_16x16x32_bf16 v[46:49], v[130:133], v[184:187], v[46:49]
	v_mfma_f32_16x16x32_bf16 v[42:45], v[138:141], v[184:187], v[42:45]
	v_mfma_f32_16x16x32_bf16 v[30:33], v[130:133], v[192:195], v[30:33]
	v_mfma_f32_16x16x32_bf16 v[26:29], v[138:141], v[192:195], v[26:29]
	v_mfma_f32_16x16x32_bf16 v[14:17], v[130:133], v[200:203], v[14:17]
	v_mfma_f32_16x16x32_bf16 v[10:13], v[138:141], v[200:203], v[10:13]
	v_mfma_f32_16x16x32_bf16 v[62:65], v[134:137], v[180:183], v[62:65]
	v_mfma_f32_16x16x32_bf16 v[58:61], v[156:159], v[180:183], v[58:61]
	v_mfma_f32_16x16x32_bf16 v[46:49], v[134:137], v[188:191], v[46:49]
	v_mfma_f32_16x16x32_bf16 v[42:45], v[156:159], v[188:191], v[42:45]
	v_mfma_f32_16x16x32_bf16 v[30:33], v[134:137], v[196:199], v[30:33]
	v_mfma_f32_16x16x32_bf16 v[26:29], v[156:159], v[196:199], v[26:29]
	v_mfma_f32_16x16x32_bf16 v[14:17], v[134:137], v[226:229], v[14:17]
	v_mfma_f32_16x16x32_bf16 v[10:13], v[156:159], v[226:229], v[10:13]
	s_setprio 0
	s_setprio 1
	v_mfma_f32_16x16x32_bf16 v[54:57], v[160:163], v[176:179], v[54:57]
	v_mfma_f32_16x16x32_bf16 v[50:53], v[168:171], v[176:179], v[50:53]
	v_mfma_f32_16x16x32_bf16 v[38:41], v[160:163], v[184:187], v[38:41]
	v_mfma_f32_16x16x32_bf16 v[34:37], v[168:171], v[184:187], v[34:37]
	v_mfma_f32_16x16x32_bf16 v[22:25], v[160:163], v[192:195], v[22:25]
	v_mfma_f32_16x16x32_bf16 v[18:21], v[168:171], v[192:195], v[18:21]
	v_mfma_f32_16x16x32_bf16 v[6:9], v[160:163], v[200:203], v[6:9]
	v_mfma_f32_16x16x32_bf16 v[2:5], v[168:171], v[200:203], v[2:5]
	v_mfma_f32_16x16x32_bf16 v[54:57], v[164:167], v[180:183], v[54:57]
	v_mfma_f32_16x16x32_bf16 v[50:53], v[172:175], v[180:183], v[50:53]
	v_mfma_f32_16x16x32_bf16 v[38:41], v[164:167], v[188:191], v[38:41]
	v_mfma_f32_16x16x32_bf16 v[34:37], v[172:175], v[188:191], v[34:37]
	v_mfma_f32_16x16x32_bf16 v[22:25], v[164:167], v[196:199], v[22:25]
	v_mfma_f32_16x16x32_bf16 v[18:21], v[172:175], v[196:199], v[18:21]
	v_mfma_f32_16x16x32_bf16 v[6:9], v[164:167], v[226:229], v[6:9]
	v_mfma_f32_16x16x32_bf16 v[2:5], v[172:175], v[226:229], v[2:5]
	s_setprio 0
	s_barrier
	s_add_u32 s57, s57, 0x100
	s_addc_u32 vcc_lo, vcc_lo, 0
	s_add_u32 s38, s38, 0x100
	s_addc_u32 s39, s39, 0
	s_cmp_ge_u32 s52, s22
	s_mov_b32 s10, s52
	s_cbranch_scc0 .LBB0_692
